# v49 + odd-attention loop edge: fragment ds_reads issued right after the step barrier, LDS-DMA issue block for step s+3 moved behind them
# baseline (speedup 1.0000x reference)
; DI void attn_group4(f32x4 (&o)[4][4], const float (&mref)[4], float (&ls)[4], const bf16x8 (&q)[4][2], bf16x8 k00, bf16x8 k01, bf16x8 k10, bf16x8 k11,
;                     bf16x8 v0, bf16x8 v1, bf16x8 v2, bf16x8 v3) {
;     const f32x4 z = {0.f, 0.f, 0.f, 0.f};
;     constexpr float C = 0.125f * LOG2E;
;     f32x4 s0[4], s1[4];
;     __builtin_amdgcn_s_setprio(1);
; #pragma unroll
;     for (int h = 0; h < 4; ++h) { s0[h] = MFMA16(k00, q[h][0], z); s1[h] = MFMA16(k10, q[h][0], z); }
; #pragma unroll
;     for (int h = 0; h < 4; ++h) { s0[h] = MFMA16(k01, q[h][1], s0[h]); s1[h] = MFMA16(k11, q[h][1], s1[h]); }
;     __builtin_amdgcn_s_setprio(0);
;     bf16x8 pb[4];
; #pragma unroll
;     for (int h = 0; h < 4; ++h) {
;         f32x4 p0, p1;
; #pragma unroll
;         for (int e = 0; e < 4; ++e) { p0[e] = __builtin_amdgcn_exp2f(__builtin_fmaf(s0[h][e], C, -mref[h])); p1[e] = __builtin_amdgcn_exp2f(__builtin_fmaf(s1[h][e], C, -mref[h])); }
;         ls[h] += ((p0[0] + p0[1]) + (p0[2] + p0[3])) + ((p1[0] + p1[1]) + (p1[2] + p1[3]));
;         u32x4 pw; pw.x = pk2(p0[0], p0[1]); pw.y = pk2(p0[2], p0[3]); pw.z = pk2(p1[0], p1[1]); pw.w = pk2(p1[2], p1[3]);
;         pb[h] = __builtin_bit_cast(bf16x8, pw);
;     }
;     __builtin_amdgcn_s_setprio(1);
; #pragma unroll
;     for (int h = 0; h < 4; ++h) { o[h][0] = MFMA16(v0, pb[h], o[h][0]); o[h][1] = MFMA16(v1, pb[h], o[h][1]); o[h][2] = MFMA16(v2, pb[h], o[h][2]); o[h][3] = MFMA16(v3, pb[h], o[h][3]); }
;     __builtin_amdgcn_s_setprio(0);
; }
; DI void attn_odd_lds(Frame& F, const float* gk  , const float* gq  , bool with_ctx) {
;     ...
;         for (int s = 0; s < n; ++s) {
;             if (s + 2 < n) AT_WAIT_BAR(4); else if (s + 1 < n) AT_WAIT_BAR(2); else AT_WAIT_BAR(0);
;             if (s + 3 < n) AT_ISSUE(s + 3);
;             const LAS unsigned char* sk = F.lds + (s & 3) * AT_SLOT + bk; const LAS unsigned char* sv = F.lds + (s & 3) * AT_SLOT + bv;
; #pragma unroll
;             for (int hf = 0; hf < 2; ++hf) {
;                 const bf16x8 k00 = LDS_K(sk, hf * 32, 0, 0), k01 = LDS_K(sk, hf * 32, 0, 1), k10 = LDS_K(sk, hf * 32, 1, 0), k11 = LDS_K(sk, hf * 32, 1, 1);
;                 const bf16x8 v0 = LDS_V(sv, 0, hf * 4), v1 = LDS_V(sv, 1, hf * 4), v2 = LDS_V(sv, 2, hf * 4), v3 = LDS_V(sv, 3, hf * 4);
;                 attn_group4(o, mx, ls, q, k00, k01, k10, k11, v0, v1, v2, v3);
;             }
.LBB0_258:
	s_and_b32 s4, s17, 3
	s_mulk_i32 s4, 0x4800
	v_add_u32_e32 v98, s4, v131
	v_add_u32_e32 v165, v98, v127
	v_add3_u32 v168, v98, v128, v129
	ds_read_b128 v[98:101], v165
	ds_read_b128 v[108:111], v165 offset:512
	ds_read_b128 v[112:115], v165 offset:2304
	ds_read_b128 v[116:119], v165 offset:2816
	v_add_u32_e32 v195, 0x2000, v168
	v_add_u32_e32 v140, 0x2800, v168
	v_add_u32_e32 v144, 0x3000, v168
	v_add_u32_e32 v148, 0x3c00, v168
	ds_read2_b64 v[136:139], v195 offset0:128 offset1:160
	ds_read2_b64 v[140:143], v140 offset0:160 offset1:192
	ds_read2_b64 v[144:147], v144 offset0:192 offset1:224
	ds_read2_b64 v[148:151], v148 offset0:96 offset1:128
	s_add_i32 s4, s17, 3
	s_cmp_ge_u32 s4, s33
	s_cbranch_scc1 .Latto_nodma
	s_cmp_lt_u32 s4, s18
	s_cselect_b64 s[40:41], -1, 0
	s_and_b64 s[46:47], s[40:41], exec
	s_cselect_b32 s5, 0, s18
	s_sub_i32 s12, s17, s5
	s_add_i32 s12, s12, 3
	s_and_b64 s[46:47], s[40:41], exec
	s_cselect_b32 s20, s19, s10
	s_mul_hi_u32 s29, s12, 0x38000
	s_mul_i32 s12, s12, 0x38000
	s_cselect_b32 s13, s22, s28
	s_add_u32 s46, s20, s12
	s_addc_u32 s47, s13, s29
	s_and_b64 s[40:41], s[40:41], exec
	s_cselect_b32 s12, s26, s31
	s_cselect_b32 s13, s11, s30
	s_lshl_b32 s5, s5, 6
	s_sub_i32 s20, s39, s5
	s_lshl_b64 s[40:41], s[20:21], 1
	s_add_u32 s40, s13, s40
	s_addc_u32 s41, s12, s41
	s_and_b32 s4, s4, 3
	s_mulk_i32 s4, 0x4800
	s_add_i32 s4, s4, s80
	s_mov_b32 s5, m0
	s_mov_b32 m0, s4
	s_nop 0
	global_load_lds_dwordx4 v124, s[46:47]
	s_mov_b32 m0, s5
	s_addk_i32 s4, 0x2400
	s_mov_b32 s5, m0
	s_mov_b32 m0, s4
	s_nop 0
	global_load_lds_dwordx4 v125, s[40:41]
	s_mov_b32 m0, s5
.Latto_nodma:
	s_setprio 1
	s_waitcnt lgkmcnt(7)
	v_mfma_f32_16x16x32_bf16 v[152:155], v[98:101], v[2:5], v[228:231]
	s_waitcnt lgkmcnt(5)
	v_mfma_f32_16x16x32_bf16 v[156:159], v[112:115], v[2:5], v[228:231]
	v_mfma_f32_16x16x32_bf16 v[170:173], v[98:101], v[10:13], v[232:235]
	v_mfma_f32_16x16x32_bf16 v[174:177], v[112:115], v[10:13], v[232:235]
	v_mfma_f32_16x16x32_bf16 v[188:191], v[98:101], v[18:21], v[236:239]
	v_mfma_f32_16x16x32_bf16 v[196:199], v[112:115], v[18:21], v[236:239]
	v_mfma_f32_16x16x32_bf16 v[98:101], v[98:101], v[42:45], v[240:243]
	v_mfma_f32_16x16x32_bf16 v[112:115], v[112:115], v[42:45], v[240:243]
	v_mfma_f32_16x16x32_bf16 v[152:155], v[108:111], v[6:9], v[152:155]
	s_waitcnt lgkmcnt(4)
	v_mfma_f32_16x16x32_bf16 v[156:159], v[116:119], v[6:9], v[156:159]
	v_mfma_f32_16x16x32_bf16 v[170:173], v[108:111], v[14:17], v[170:173]
	v_mfma_f32_16x16x32_bf16 v[174:177], v[116:119], v[14:17], v[174:177]
	v_mfma_f32_16x16x32_bf16 v[188:191], v[108:111], v[22:25], v[188:191]
	v_mfma_f32_16x16x32_bf16 v[196:199], v[116:119], v[22:25], v[196:199]
	v_mfma_f32_16x16x32_bf16 v[98:101], v[108:111], v[46:49], v[98:101]
	v_mfma_f32_16x16x32_bf16 v[200:203], v[116:119], v[46:49], v[112:115]
	s_setprio 0
	v_exp_f32_e32 v161, v152
	v_exp_f32_e32 v167, v156
	v_exp_f32_e32 v179, v153
	v_exp_f32_e32 v185, v157
	v_exp_f32_e32 v213, v154
	v_exp_f32_e32 v215, v158
	v_exp_f32_e32 v217, v155
	v_exp_f32_e32 v219, v159
	v_exp_f32_e32 v160, v170
	v_exp_f32_e32 v166, v174
	v_exp_f32_e32 v178, v171
	v_exp_f32_e32 v184, v175
	v_exp_f32_e32 v212, v172
	v_exp_f32_e32 v214, v176
	v_exp_f32_e32 v216, v173
	v_exp_f32_e32 v218, v177
	v_exp_f32_e32 v117, v188
	v_exp_f32_e32 v109, v196
	v_exp_f32_e32 v221, v189
	v_exp_f32_e32 v113, v197
	v_exp_f32_e32 v119, v190
	v_exp_f32_e32 v111, v198
	v_exp_f32_e32 v223, v191
	v_exp_f32_e32 v116, v98
	v_exp_f32_e32 v115, v199
	v_exp_f32_e32 v108, v200
	v_exp_f32_e32 v220, v99
	v_exp_f32_e32 v112, v201
	v_exp_f32_e32 v118, v100
	v_exp_f32_e32 v110, v202
	v_exp_f32_e32 v222, v101
	v_exp_f32_e32 v114, v203
	v_cvt_pk_bf16_f32 v152, v161, v179
	v_cvt_pk_bf16_f32 v153, v213, v217
	v_cvt_pk_bf16_f32 v154, v167, v185
	v_cvt_pk_bf16_f32 v155, v215, v219
	v_cvt_pk_bf16_f32 v156, v160, v178
	v_cvt_pk_bf16_f32 v157, v212, v216
	v_cvt_pk_bf16_f32 v158, v166, v184
	v_cvt_pk_bf16_f32 v159, v214, v218
	v_cvt_pk_bf16_f32 v170, v117, v221
	v_cvt_pk_bf16_f32 v171, v119, v223
	v_cvt_pk_bf16_f32 v172, v109, v113
	v_cvt_pk_bf16_f32 v173, v111, v115
	v_cvt_pk_bf16_f32 v98, v116, v220
	v_cvt_pk_bf16_f32 v99, v118, v222
	v_cvt_pk_bf16_f32 v100, v108, v112
	v_cvt_pk_bf16_f32 v101, v110, v114
	s_setprio 1
	s_waitcnt lgkmcnt(3)
	v_mfma_f32_16x16x32_bf16 v[94:97], v[136:139], v[152:155], v[94:97]
	s_waitcnt lgkmcnt(2)
	v_mfma_f32_16x16x32_bf16 v[90:93], v[140:143], v[152:155], v[90:93]
	s_waitcnt lgkmcnt(1)
	v_mfma_f32_16x16x32_bf16 v[86:89], v[144:147], v[152:155], v[86:89]
	s_waitcnt lgkmcnt(0)
	v_mfma_f32_16x16x32_bf16 v[82:85], v[148:151], v[152:155], v[82:85]
	v_mfma_f32_16x16x32_bf16 v[78:81], v[136:139], v[156:159], v[78:81]
	v_mfma_f32_16x16x32_bf16 v[74:77], v[140:143], v[156:159], v[74:77]
	v_mfma_f32_16x16x32_bf16 v[70:73], v[144:147], v[156:159], v[70:73]
	v_mfma_f32_16x16x32_bf16 v[66:69], v[148:151], v[156:159], v[66:69]
	v_mfma_f32_16x16x32_bf16 v[62:65], v[136:139], v[170:173], v[62:65]
	v_mfma_f32_16x16x32_bf16 v[58:61], v[140:143], v[170:173], v[58:61]
	v_mfma_f32_16x16x32_bf16 v[54:57], v[144:147], v[170:173], v[54:57]
	v_mfma_f32_16x16x32_bf16 v[50:53], v[148:151], v[170:173], v[50:53]
	v_mfma_f32_16x16x32_bf16 v[38:41], v[136:139], v[98:101], v[38:41]
	v_mfma_f32_16x16x32_bf16 v[34:37], v[140:143], v[98:101], v[34:37]
	v_mfma_f32_16x16x32_bf16 v[30:33], v[144:147], v[98:101], v[30:33]
	v_mfma_f32_16x16x32_bf16 v[26:29], v[148:151], v[98:101], v[26:29]
	s_setprio 0
	ds_read_b128 v[136:139], v165 offset:4608
	ds_read_b128 v[140:143], v165 offset:5120
	ds_read_b128 v[144:147], v165 offset:6912
	ds_read_b128 v[148:151], v165 offset:7424
	ds_read2_b64 v[98:101], v195 offset0:192 offset1:224
	v_add_u32_e32 v152, 0x2c00, v168
	v_add_u32_e32 v156, 0x3800, v168
	v_add_u32_e32 v165, 0x4000, v168
	ds_read2_b64 v[152:155], v152 offset0:96 offset1:128
	ds_read2_b64 v[156:159], v156 offset1:32
	ds_read2_b64 v[170:173], v165 offset0:32 offset1:64
	s_setprio 1
	s_waitcnt lgkmcnt(7)
; DI unsigned pk2(float lo, float hi) { f32x2 v = {lo, hi}; bf16x2_t b = __builtin_convertvector(v, bf16x2_t); return __builtin_bit_cast(unsigned, b); }
; #define MFMA16(a, b, c) __builtin_amdgcn_mfma_f32_16x16x32_bf16((a), (b), (c), 0, 0, 0)
; #define LDS_V(sv, db, cb) lds_v((sv), 2 * (db) * AT_GRP + (cb) * 128)
; DI void attn_group4(f32x4 (&o)[4][4], const float (&mref)[4], float (&ls)[4], const bf16x8 (&q)[4][2], bf16x8 k00, bf16x8 k01, bf16x8 k10, bf16x8 k11,
;                     bf16x8 v0, bf16x8 v1, bf16x8 v2, bf16x8 v3) {
;     const f32x4 z = {0.f, 0.f, 0.f, 0.f};
;     constexpr float C = 0.125f * LOG2E;
;     f32x4 s0[4], s1[4];
;     __builtin_amdgcn_s_setprio(1);
; #pragma unroll
;     for (int h = 0; h < 4; ++h) { s0[h] = MFMA16(k00, q[h][0], z); s1[h] = MFMA16(k10, q[h][0], z); }
; #pragma unroll
;     for (int h = 0; h < 4; ++h) { s0[h] = MFMA16(k01, q[h][1], s0[h]); s1[h] = MFMA16(k11, q[h][1], s1[h]); }
;     __builtin_amdgcn_s_setprio(0);
;     bf16x8 pb[4];
; #pragma unroll
;     for (int h = 0; h < 4; ++h) {
;         f32x4 p0, p1;
; #pragma unroll
;         for (int e = 0; e < 4; ++e) { p0[e] = __builtin_amdgcn_exp2f(__builtin_fmaf(s0[h][e], C, -mref[h])); p1[e] = __builtin_amdgcn_exp2f(__builtin_fmaf(s1[h][e], C, -mref[h])); }
;         ls[h] += ((p0[0] + p0[1]) + (p0[2] + p0[3])) + ((p1[0] + p1[1]) + (p1[2] + p1[3]));
;         u32x4 pw; pw.x = pk2(p0[0], p0[1]); pw.y = pk2(p0[2], p0[3]); pw.z = pk2(p1[0], p1[1]); pw.w = pk2(p1[2], p1[3]);
;         pb[h] = __builtin_bit_cast(bf16x8, pw);
;     }
;     __builtin_amdgcn_s_setprio(1);
; #pragma unroll
;     for (int h = 0; h < 4; ++h) { o[h][0] = MFMA16(v0, pb[h], o[h][0]); o[h][1] = MFMA16(v1, pb[h], o[h][1]); o[h][2] = MFMA16(v2, pb[h], o[h][2]); o[h][3] = MFMA16(v3, pb[h], o[h][3]); }
;     __builtin_amdgcn_s_setprio(0);
; }
; DI void attn_odd_lds(Frame& F, const float* gk  , const float* gq  , bool with_ctx) {
;     ...
;             for (int hf = 0; hf < 2; ++hf) {
;                 const bf16x8 k00 = LDS_K(sk, hf * 32, 0, 0), k01 = LDS_K(sk, hf * 32, 0, 1), k10 = LDS_K(sk, hf * 32, 1, 0), k11 = LDS_K(sk, hf * 32, 1, 1);
;                 const bf16x8 v0 = LDS_V(sv, 0, hf * 4), v1 = LDS_V(sv, 1, hf * 4), v2 = LDS_V(sv, 2, hf * 4), v3 = LDS_V(sv, 3, hf * 4);
;                 attn_group4(o, mx, ls, q, k00, k01, k10, k11, v0, v1, v2, v3);
;             }
;         }
	v_mfma_f32_16x16x32_bf16 v[174:177], v[136:139], v[2:5], v[228:231]
	s_waitcnt lgkmcnt(5)
	v_mfma_f32_16x16x32_bf16 v[188:191], v[144:147], v[2:5], v[228:231]
	v_mfma_f32_16x16x32_bf16 v[196:199], v[136:139], v[10:13], v[232:235]
	v_mfma_f32_16x16x32_bf16 v[200:203], v[144:147], v[10:13], v[232:235]
	v_mfma_f32_16x16x32_bf16 v[204:207], v[136:139], v[18:21], v[236:239]
	v_mfma_f32_16x16x32_bf16 v[208:211], v[144:147], v[18:21], v[236:239]
	v_mfma_f32_16x16x32_bf16 v[136:139], v[136:139], v[42:45], v[240:243]
	v_mfma_f32_16x16x32_bf16 v[144:147], v[144:147], v[42:45], v[240:243]
	v_mfma_f32_16x16x32_bf16 v[174:177], v[140:143], v[6:9], v[174:177]
	s_waitcnt lgkmcnt(4)
	v_mfma_f32_16x16x32_bf16 v[188:191], v[148:151], v[6:9], v[188:191]
	v_mfma_f32_16x16x32_bf16 v[196:199], v[140:143], v[14:17], v[196:199]
	v_mfma_f32_16x16x32_bf16 v[200:203], v[148:151], v[14:17], v[200:203]
	v_mfma_f32_16x16x32_bf16 v[204:207], v[140:143], v[22:25], v[204:207]
	v_mfma_f32_16x16x32_bf16 v[208:211], v[148:151], v[22:25], v[208:211]
	v_mfma_f32_16x16x32_bf16 v[136:139], v[140:143], v[46:49], v[136:139]
	v_mfma_f32_16x16x32_bf16 v[140:143], v[148:151], v[46:49], v[144:147]
	s_setprio 0
	s_nop 1
	v_exp_f32_e32 v149, v174
	v_exp_f32_e32 v151, v188
	v_exp_f32_e32 v175, v175
	v_exp_f32_e32 v174, v197
	v_exp_f32_e32 v189, v189
	v_exp_f32_e32 v188, v201
	v_exp_f32_e32 v225, v176
	v_exp_f32_e32 v224, v198
	v_exp_f32_e32 v227, v190
	v_exp_f32_e32 v226, v202
	v_exp_f32_e32 v177, v177
	v_exp_f32_e32 v148, v196
	v_exp_f32_e32 v176, v199
	v_pk_add_f32 v[160:161], v[160:161], v[178:179]
	v_pk_add_f32 v[178:179], v[212:213], v[216:217]
	v_exp_f32_e32 v191, v191
	v_exp_f32_e32 v150, v200
	v_exp_f32_e32 v190, v203
	v_pk_add_f32 v[160:161], v[160:161], v[178:179]
	v_pk_add_f32 v[166:167], v[166:167], v[184:185]
	v_pk_add_f32 v[178:179], v[214:215], v[218:219]
	v_cvt_pk_bf16_f32 v146, v151, v189
	v_pk_add_f32 v[166:167], v[166:167], v[178:179]
	v_pk_add_f32 v[178:179], v[226:227], v[190:191]
	v_pk_add_f32 v[160:161], v[160:161], v[166:167]
	v_pk_add_f32 v[166:167], v[224:225], v[176:177]
	v_pk_add_f32 v[106:107], v[106:107], v[160:161]
	v_pk_add_f32 v[160:161], v[148:149], v[174:175]
	v_cvt_pk_bf16_f32 v147, v227, v191
	v_pk_add_f32 v[160:161], v[160:161], v[166:167]
	v_pk_add_f32 v[166:167], v[150:151], v[188:189]
	v_pk_add_f32 v[166:167], v[166:167], v[178:179]
	v_cvt_pk_bf16_f32 v150, v150, v188
	v_pk_add_f32 v[160:161], v[160:161], v[166:167]
	v_cvt_pk_bf16_f32 v151, v226, v190
	v_pk_add_f32 v[106:107], v[106:107], v[160:161]
	v_exp_f32_e32 v161, v204
	v_exp_f32_e32 v167, v208
	v_exp_f32_e32 v179, v205
	v_exp_f32_e32 v185, v209
	v_exp_f32_e32 v189, v206
	v_exp_f32_e32 v191, v210
	v_exp_f32_e32 v197, v207
	v_exp_f32_e32 v199, v211
	v_exp_f32_e32 v160, v136
	v_exp_f32_e32 v166, v140
	v_exp_f32_e32 v178, v137
	v_exp_f32_e32 v184, v141
	v_exp_f32_e32 v188, v138
	v_exp_f32_e32 v190, v142
	v_exp_f32_e32 v196, v139
	v_exp_f32_e32 v198, v143
	v_pk_add_f32 v[116:117], v[116:117], v[220:221]
	v_pk_add_f32 v[118:119], v[118:119], v[222:223]
	v_pk_add_f32 v[108:109], v[108:109], v[112:113]
	v_pk_add_f32 v[110:111], v[110:111], v[114:115]
	v_pk_add_f32 v[116:117], v[116:117], v[118:119]
	v_pk_add_f32 v[108:109], v[108:109], v[110:111]
	v_pk_add_f32 v[110:111], v[188:189], v[196:197]
	v_pk_add_f32 v[108:109], v[116:117], v[108:109]
	v_pk_add_f32 v[112:113], v[190:191], v[198:199]
	v_pk_add_f32 v[104:105], v[104:105], v[108:109]
	v_pk_add_f32 v[108:109], v[160:161], v[178:179]
	v_cvt_pk_bf16_f32 v144, v149, v175
	v_pk_add_f32 v[108:109], v[108:109], v[110:111]
	v_pk_add_f32 v[110:111], v[166:167], v[184:185]
	v_cvt_pk_bf16_f32 v145, v225, v177
	v_pk_add_f32 v[110:111], v[110:111], v[112:113]
	v_cvt_pk_bf16_f32 v148, v148, v174
	v_pk_add_f32 v[108:109], v[108:109], v[110:111]
	v_cvt_pk_bf16_f32 v149, v224, v176
	v_pk_add_f32 v[104:105], v[104:105], v[108:109]
	v_cvt_pk_bf16_f32 v174, v161, v179
	v_cvt_pk_bf16_f32 v175, v189, v197
	v_cvt_pk_bf16_f32 v176, v167, v185
	v_cvt_pk_bf16_f32 v177, v191, v199
	v_cvt_pk_bf16_f32 v108, v160, v178
	v_cvt_pk_bf16_f32 v109, v188, v196
	v_cvt_pk_bf16_f32 v110, v166, v184
	v_cvt_pk_bf16_f32 v111, v190, v198
	s_setprio 1
	s_waitcnt lgkmcnt(3)
	v_mfma_f32_16x16x32_bf16 v[94:97], v[98:101], v[144:147], v[94:97]
	s_waitcnt lgkmcnt(2)
	v_mfma_f32_16x16x32_bf16 v[90:93], v[152:155], v[144:147], v[90:93]
	s_waitcnt lgkmcnt(1)
	v_mfma_f32_16x16x32_bf16 v[86:89], v[156:159], v[144:147], v[86:89]
	s_waitcnt lgkmcnt(0)
	v_mfma_f32_16x16x32_bf16 v[82:85], v[170:173], v[144:147], v[82:85]
	v_mfma_f32_16x16x32_bf16 v[78:81], v[98:101], v[148:151], v[78:81]
	v_mfma_f32_16x16x32_bf16 v[74:77], v[152:155], v[148:151], v[74:77]
	v_mfma_f32_16x16x32_bf16 v[70:73], v[156:159], v[148:151], v[70:73]
	v_mfma_f32_16x16x32_bf16 v[66:69], v[170:173], v[148:151], v[66:69]
	v_mfma_f32_16x16x32_bf16 v[62:65], v[98:101], v[174:177], v[62:65]
	v_mfma_f32_16x16x32_bf16 v[58:61], v[152:155], v[174:177], v[58:61]
	v_mfma_f32_16x16x32_bf16 v[54:57], v[156:159], v[174:177], v[54:57]
	v_mfma_f32_16x16x32_bf16 v[50:53], v[170:173], v[174:177], v[50:53]
	v_mfma_f32_16x16x32_bf16 v[38:41], v[98:101], v[108:111], v[38:41]
	v_mfma_f32_16x16x32_bf16 v[34:37], v[152:155], v[108:111], v[34:37]
	v_mfma_f32_16x16x32_bf16 v[30:33], v[156:159], v[108:111], v[30:33]
	v_mfma_f32_16x16x32_bf16 v[26:29], v[170:173], v[108:111], v[26:29]
	s_setprio 0
	s_add_i32 s17, s17, 1
	s_add_i32 s39, s39, 64
	s_cmp_eq_u32 s37, s17
	s_cbranch_scc1 .LBB0_240

; #define AT_WAIT_BAR(N) asm volatile("s_waitcnt vmcnt(" #N ") lgkmcnt(0)\n\ts_barrier" ::: "memory")
; DI void attn_odd_lds(Frame& F, const float* gk  , const float* gq  , bool with_ctx) {
;     ...
;             if (s + 2 < n) AT_WAIT_BAR(4); else if (s + 1 < n) AT_WAIT_BAR(2); else AT_WAIT_BAR(0);
;             if (s + 3 < n) AT_ISSUE(s + 3);
.LBB0_264:
	s_cbranch_execz .LBB0_267
.LBB0_265:
	s_branch .LBB0_258
.LBB0_266:
	s_andn2_b64 vcc, exec, s[4:5]
	s_cbranch_vccnz .LBB0_265
.LBB0_267:
	s_waitcnt vmcnt(4) lgkmcnt(0)
	s_barrier
	s_branch .LBB0_258
